# HGRN output units (phase-3 tail): norm weights loaded once per workgroup, the unit's q / accumulator / gate loads issued behind the state loads, straight-line epilogue instead of a load-wait ladder
# speedup vs baseline: 1.0177x; 1.0136x over previous
; #define LAS __attribute__((address_space(3)))
; template <class Tp> DEV Tp* wsp(const Frame& F, size_t off) { return (Tp*)(F.ws + off); }
; DEV void hgrn_c_unit(Frame& F, int c, int hp) {
;     ...
;     const int tid = F.tid, w = F.wave, lane = F.lane, n = lane & 15, q4 = lane >> 4;
;     { const bf16* HL = wsp<bf16>(F, WS_HL) + (size_t)(c * 4 + 2 * hp) * 16384;
; #pragma unroll
;       for (int j = 0; j < 8; ++j) { const int e8 = tid + 512 * j; const v4u v = *(const v4u*)(HL + 8 * e8); const int hh = e8 >> 11, rem = e8 & 2047, kr = rem >> 4, vc = (rem & 15) * 8;
;           *(LAS v4u*)(L + hh * 128 * HC_SROW + kr * HC_SROW + 2 * vc) = v; } }
;     __syncthreads();
;     const int h = 2 * hp + (w >> 2), ti = w & 3; const size_t row = (size_t)c * 64 + 16 * ti + n;
;     const LAS unsigned char* Sb = L + (w >> 2) * 128 * HC_SROW;
;     const bf16* qp = wsp<bf16>(F, WS_HQT) + row * 512 + h * 128 + 8 * q4;
;     f32x4 acc[8];
; #pragma unroll
;     for (int vt = 0; vt < 8; ++vt) acc[vt] = *(const f32x4*)(wsp<float>(F, WS_HIN) + row * 512 + h * 128 + 16 * vt + 4 * q4);
; #pragma unroll
;     for (int ks = 0; ks < 4; ++ks) { const ab8 qf = *(const ab8*)(qp + 32 * ks);
; #pragma unroll
;         for (int vt = 0; vt < 8; ++vt) { const ab8 sf = tr_frag(Sb, 32 * ks, 32 * vt, n, q4, HC_SROW); acc[vt] = __builtin_amdgcn_mfma_f32_16x16x32_bf16(sf, qf, acc[vt], 0, 0, 0); } }
;     float ss = 0.f;
; #pragma unroll
;     for (int vt = 0; vt < 8; ++vt) ss += (acc[vt][0] * acc[vt][0] + acc[vt][1] * acc[vt][1]) + (acc[vt][2] * acc[vt][2] + acc[vt][3] * acc[vt][3]);
;     ss += __shfl_xor(ss, 16); ss += __shfl_xor(ss, 32);
;     const float rr = 1.0f / sqrtf(ss * (1.f / 128.f) + EPS);
;     const bf16* HG = wsp<bf16>(F, WS_HG) + row * 512 + h * 128 + 4 * q4; bf16* OB = wsp<bf16>(F, WS_OB) + row * 512 + h * 128 + 4 * q4; const float* gn = ((const float*)F.A.in[20]) + 4 * q4;
; #pragma unroll
;     for (int vt = 0; vt < 8; ++vt) { const v2u gw_ = *(const v2u*)(HG + 16 * vt); const f32x4 g4 = *(const f32x4*)(gn + 16 * vt);
.LBB0_1683:
	v_lshlrev_b32_e32 v2, 4, v138
	v_and_b32_e32 v3, 0xf0, v2
	v_lshrrev_b32_e32 v2, 4, v138
	v_bfe_u32 v4, v138, 4, 7
	v_and_b32_e32 v2, 0x7ffff80, v2
	s_movk_i32 s2, 0x120
	v_mul_lo_u32 v2, v2, s2
	v_mul_u32_u24_e32 v4, 0x120, v4
	v_add3_u32 v5, 0, v2, v4
	v_add_u32_e32 v2, 0x200, v138
	v_lshrrev_b32_e32 v6, 4, v2
	v_lshlrev_b32_e32 v36, 3, v2
	v_bfe_u32 v2, v2, 4, 7
	v_and_b32_e32 v6, 0x7ffff80, v6
	v_mul_lo_u32 v6, v6, s2
	v_mul_u32_u24_e32 v2, 0x120, v2
	v_add3_u32 v6, 0, v6, v2
	v_add_u32_e32 v2, 0x400, v138
	v_lshrrev_b32_e32 v7, 4, v2
	v_lshlrev_b32_e32 v38, 3, v2
	v_bfe_u32 v2, v2, 4, 7
	v_and_b32_e32 v7, 0x7ffff80, v7
	v_mul_lo_u32 v7, v7, s2
	v_mul_u32_u24_e32 v2, 0x120, v2
	v_add3_u32 v7, 0, v7, v2
	v_add_u32_e32 v2, 0x600, v138
	v_lshrrev_b32_e32 v8, 4, v2
	v_lshlrev_b32_e32 v40, 3, v2
	v_bfe_u32 v2, v2, 4, 7
	v_and_b32_e32 v8, 0x7ffff80, v8
	v_mul_lo_u32 v8, v8, s2
	v_mul_u32_u24_e32 v2, 0x120, v2
	v_add3_u32 v8, 0, v8, v2
	v_add_u32_e32 v2, 0x800, v138
	v_lshlrev_b32_e32 v42, 3, v2
	v_lshrrev_b32_e32 v2, 4, v2
	v_and_b32_e32 v2, 0x7ffff80, v2
	v_mul_lo_u32 v2, v2, s2
	v_add3_u32 v4, 0, v2, v4
	v_add_u32_e32 v2, 0xa00, v138
	v_lshrrev_b32_e32 v9, 4, v2
	v_lshlrev_b32_e32 v44, 3, v2
	v_bfe_u32 v2, v2, 4, 7
	v_and_b32_e32 v9, 0x7ffff80, v9
	v_mul_lo_u32 v9, v9, s2
	v_mul_u32_u24_e32 v2, 0x120, v2
	v_add3_u32 v9, 0, v9, v2
	v_add_u32_e32 v2, 0xc00, v138
	v_lshrrev_b32_e32 v10, 4, v2
	v_lshlrev_b32_e32 v46, 3, v2
	v_bfe_u32 v2, v2, 4, 7
	v_and_b32_e32 v10, 0x7ffff80, v10
	v_mul_lo_u32 v10, v10, s2
	v_mul_u32_u24_e32 v2, 0x120, v2
	s_add_u32 s10, s72, 0x10f00
	v_add3_u32 v10, 0, v10, v2
	v_add_u32_e32 v2, 0xe00, v138
	s_addc_u32 s11, s73, 0
	v_lshrrev_b32_e32 v11, 4, v2
	s_add_u32 s20, s72, 0x25c00000
	v_and_b32_e32 v11, 0x7ffff80, v11
	v_and_b32_e32 v1, 15, v138
	s_addc_u32 s21, s73, 0
	v_lshlrev_b32_e32 v48, 3, v2
	v_bfe_u32 v2, v2, 4, 7
	v_mul_lo_u32 v11, v11, s2
	s_lshl_b32 s2, s79, 4
	v_mul_u32_u24_e32 v2, 0x120, v2
	v_lshrrev_b32_e32 v12, 4, v159
	v_and_or_b32 v13, s2, 48, v1
	v_readlane_b32 s2, v249, 35
	v_add3_u32 v11, 0, v11, v2
	s_mul_i32 s2, s2, 0x9000
	v_lshlrev_b32_e32 v2, 3, v12
	s_add_u32 s12, s72, 0x29d00000
	v_bfe_u32 v1, v138, 2, 2
	v_lshlrev_b32_e32 v34, 3, v138
	s_addc_u32 s13, s73, 0
	s_add_i32 s2, s2, 0
	v_or_b32_e32 v1, v2, v1
	v_readlane_b32 s48, v250, 26
	v_mov_b32_e32 v51, 0
	v_lshlrev_b32_e32 v52, 2, v12
	s_add_u32 s14, s72, 0x2bd00000
	v_and_b32_e32 v12, 24, v34
	v_mul_u32_u24_e32 v1, 0x120, v1
	v_and_b32_e32 v50, 48, v159
	v_readlane_b32 s56, v250, 34
	v_readlane_b32 s57, v250, 35
	v_readlane_b32 s28, v249, 13
	v_ashrrev_i32_e32 v35, 31, v34
	v_ashrrev_i32_e32 v37, 31, v36
	v_ashrrev_i32_e32 v39, 31, v38
	v_ashrrev_i32_e32 v41, 31, v40
	v_ashrrev_i32_e32 v43, 31, v42
	v_ashrrev_i32_e32 v45, 31, v44
	v_ashrrev_i32_e32 v47, 31, v46
	v_ashrrev_i32_e32 v49, 31, v48
	s_addc_u32 s15, s73, 0
	v_add3_u32 v1, s2, v12, v1
	v_lshl_add_u64 v[54:55], s[56:57], 0, v[50:51]
	v_lshlrev_b32_e32 v56, 9, v13
	s_mov_b64 s[4:5], 0
	s_add_i32 s22, 0, 0x22020
	s_movk_i32 s23, 0x1ff
	v_add_u32_e32 v53, v5, v3
	v_add_u32_e32 v57, v6, v3
	v_add_u32_e32 v63, v7, v3
	v_add_u32_e32 v66, v8, v3
	v_add_u32_e32 v67, v4, v3
	v_add_u32_e32 v68, v9, v3
	v_add_u32_e32 v69, v10, v3
	v_add_u32_e32 v70, v11, v3
	v_lshlrev_b32_e32 v58, 1, v2
	v_mov_b32_e32 v71, 0x358637bd
	s_mov_b32 s24, 0xf800000
	v_mov_b32_e32 v72, 0x260
	v_readlane_b32 s96, v249, 15
	v_readlane_b32 s29, v249, 14
	v_readlane_b32 s49, v250, 27
	v_readlane_b32 s50, v250, 28
	v_readlane_b32 s51, v250, 29
	v_readlane_b32 s52, v250, 30
	v_readlane_b32 s53, v250, 31
	v_readlane_b32 s54, v250, 32
	v_readlane_b32 s55, v250, 33
	v_readlane_b32 s58, v250, 36
	v_readlane_b32 s59, v250, 37
	v_readlane_b32 s60, v250, 38
	v_readlane_b32 s61, v250, 39
	v_readlane_b32 s62, v250, 40
	v_readlane_b32 s63, v250, 41
	global_load_dwordx4 v[160:163], v[54:55], off
	global_load_dwordx4 v[164:167], v[54:55], off offset:64
	global_load_dwordx4 v[168:171], v[54:55], off offset:128
	global_load_dwordx4 v[172:175], v[54:55], off offset:192
	global_load_dwordx4 v[176:179], v[54:55], off offset:256
	global_load_dwordx4 v[180:183], v[54:55], off offset:320
	global_load_dwordx4 v[184:187], v[54:55], off offset:384
	global_load_dwordx4 v[188:191], v[54:55], off offset:448
	s_branch .LBB0_1688

; #define LAS __attribute__((address_space(3)))
; template <class Tp> DEV Tp* wsp(const Frame& F, size_t off) { return (Tp*)(F.ws + off); }
; DEV void hgrn_c_unit(Frame& F, int c, int hp) {
;     ...
;     { const bf16* HL = wsp<bf16>(F, WS_HL) + (size_t)(c * 4 + 2 * hp) * 16384;
; #pragma unroll
;       for (int j = 0; j < 8; ++j) { const int e8 = tid + 512 * j; const v4u v = *(const v4u*)(HL + 8 * e8); const int hh = e8 >> 11, rem = e8 & 2047, kr = rem >> 4, vc = (rem & 15) * 8;
;           *(LAS v4u*)(L + hh * 128 * HC_SROW + kr * HC_SROW + 2 * vc) = v; } }
;     __syncthreads();
;     const int h = 2 * hp + (w >> 2), ti = w & 3; const size_t row = (size_t)c * 64 + 16 * ti + n;
;     const LAS unsigned char* Sb = L + (w >> 2) * 128 * HC_SROW;
;     const bf16* qp = wsp<bf16>(F, WS_HQT) + row * 512 + h * 128 + 8 * q4;
;     f32x4 acc[8];
; #pragma unroll
;     for (int vt = 0; vt < 8; ++vt) acc[vt] = *(const f32x4*)(wsp<float>(F, WS_HIN) + row * 512 + h * 128 + 16 * vt + 4 * q4);
; #pragma unroll
;     for (int ks = 0; ks < 4; ++ks) { const ab8 qf = *(const ab8*)(qp + 32 * ks);
; #pragma unroll
;         for (int vt = 0; vt < 8; ++vt) { const ab8 sf = tr_frag(Sb, 32 * ks, 32 * vt, n, q4, HC_SROW); acc[vt] = __builtin_amdgcn_mfma_f32_16x16x32_bf16(sf, qf, acc[vt], 0, 0, 0); } }
.LBB0_1686:
	s_ashr_i32 s4, s18, 1
	s_lshl_b32 s16, s18, 1
	s_lshl_b32 s5, s4, 2
	s_and_b32 s18, s16, 2
	s_or_b32 s16, s18, s5
	s_ashr_i32 s17, s16, 31
	s_lshl_b64 s[16:17], s[16:17], 15
	s_add_u32 s16, s20, s16
	s_addc_u32 s17, s21, s17
	v_lshl_add_u64 v[2:3], v[34:35], 1, s[16:17]
	v_lshl_add_u64 v[6:7], v[36:37], 1, s[16:17]
	v_lshl_add_u64 v[10:11], v[38:39], 1, s[16:17]
	v_lshl_add_u64 v[14:15], v[40:41], 1, s[16:17]
	v_lshl_add_u64 v[18:19], v[42:43], 1, s[16:17]
	v_lshl_add_u64 v[22:23], v[44:45], 1, s[16:17]
	v_lshl_add_u64 v[26:27], v[46:47], 1, s[16:17]
	v_lshl_add_u64 v[30:31], v[48:49], 1, s[16:17]
	global_load_dwordx4 v[2:5], v[2:3], off
	s_nop 0
	global_load_dwordx4 v[6:9], v[6:7], off
	s_nop 0
	global_load_dwordx4 v[10:13], v[10:11], off
	s_nop 0
	global_load_dwordx4 v[14:17], v[14:15], off
	s_nop 0
	global_load_dwordx4 v[18:21], v[18:19], off
	s_nop 0
	global_load_dwordx4 v[22:25], v[22:23], off
	s_nop 0
	global_load_dwordx4 v[26:29], v[26:27], off
	s_nop 0
	global_load_dwordx4 v[30:33], v[30:31], off
	v_readlane_b32 s5, v249, 35
	s_add_i32 s18, s18, s5
	s_ashr_i32 s5, s4, 31
	s_lshl_b64 s[4:5], s[4:5], 15
	s_lshl_b32 s18, s18, 7
	v_mov_b32_e32 v61, s5
	v_or_b32_e32 v60, s4, v56
	s_ashr_i32 s19, s18, 31
	v_lshl_add_u64 v[64:65], v[60:61], 2, s[12:13]
	v_lshlrev_b64 v[60:61], 1, v[60:61]
	s_lshl_b64 s[16:17], s[18:19], 1
	v_lshl_add_u64 v[74:75], s[14:15], 0, v[60:61]
	v_mov_b32_e32 v59, v51
	v_lshl_add_u64 v[74:75], v[74:75], 0, s[16:17]
	v_lshlrev_b32_e32 v50, 2, v52
	v_lshl_add_u64 v[64:65], s[18:19], 2, v[64:65]
	v_lshl_add_u64 v[98:99], v[74:75], 0, v[58:59]
	v_lshl_add_u64 v[64:65], v[64:65], 0, v[50:51]
	v_lshl_add_u64 v[132:133], s[6:7], 0, v[60:61]
	v_lshl_add_u64 v[132:133], v[132:133], 0, s[16:17]
	v_lshlrev_b32_e32 v134, 1, v52
	v_mov_b32_e32 v135, 0
	v_lshl_add_u64 v[132:133], v[132:133], 0, v[134:135]
	global_load_dwordx4 v[100:103], v[98:99], off
	global_load_dwordx4 v[104:107], v[98:99], off offset:64
	global_load_dwordx4 v[108:111], v[98:99], off offset:128
	global_load_dwordx4 v[112:115], v[98:99], off offset:192
	global_load_dwordx4 v[192:195], v[64:65], off
	global_load_dwordx4 v[196:199], v[64:65], off offset:64
	global_load_dwordx4 v[200:203], v[64:65], off offset:128
	global_load_dwordx4 v[204:207], v[64:65], off offset:192
	global_load_dwordx4 v[208:211], v[64:65], off offset:256
	global_load_dwordx4 v[212:215], v[64:65], off offset:320
	global_load_dwordx4 v[216:219], v[64:65], off offset:384
	global_load_dwordx4 v[220:223], v[64:65], off offset:448
	global_load_dwordx2 v[116:117], v[132:133], off
	global_load_dwordx2 v[118:119], v[132:133], off offset:32
	global_load_dwordx2 v[120:121], v[132:133], off offset:64
	global_load_dwordx2 v[122:123], v[132:133], off offset:96
	global_load_dwordx2 v[124:125], v[132:133], off offset:128
	global_load_dwordx2 v[126:127], v[132:133], off offset:160
	global_load_dwordx2 v[128:129], v[132:133], off offset:192
	global_load_dwordx2 v[130:131], v[132:133], off offset:224
	s_waitcnt vmcnt(27)
	ds_write_b128 v53, v[2:5]
	s_waitcnt vmcnt(26)
	ds_write_b128 v57, v[6:9]
	s_waitcnt vmcnt(25)
	ds_write_b128 v63, v[10:13]
	s_waitcnt vmcnt(24)
	ds_write_b128 v66, v[14:17]
	s_waitcnt vmcnt(23)
	ds_write_b128 v67, v[18:21]
	s_waitcnt vmcnt(22)
	ds_write_b128 v68, v[22:25]
	s_waitcnt vmcnt(21)
	ds_write_b128 v69, v[26:29]
	s_waitcnt vmcnt(20)
	ds_write_b128 v70, v[30:33]
	s_waitcnt lgkmcnt(0)
	s_barrier
	s_waitcnt vmcnt(8)
	ds_read_b64_tr_b16 v[16:17], v1 offset:1152
	ds_read_b64_tr_b16 v[14:15], v1
	ds_read_b64_tr_b16 v[28:29], v1 offset:1184
	ds_read_b64_tr_b16 v[26:27], v1 offset:32
	ds_read_b64_tr_b16 v[30:31], v1 offset:64
	ds_read_b64_tr_b16 v[74:75], v1 offset:96
	ds_read_b64_tr_b16 v[32:33], v1 offset:1216
	ds_read_b64_tr_b16 v[76:77], v1 offset:1248
	ds_read_b64_tr_b16 v[82:83], v1 offset:128
	s_waitcnt lgkmcnt(7)
	v_mfma_f32_16x16x32_bf16 v[6:9], v[14:17], v[100:103], v[192:195]
	s_waitcnt lgkmcnt(5)
	v_mfma_f32_16x16x32_bf16 v[10:13], v[26:29], v[100:103], v[196:199]
	s_waitcnt lgkmcnt(2)
	v_mfma_f32_16x16x32_bf16 v[18:21], v[30:33], v[100:103], v[200:203]
	ds_read_b64_tr_b16 v[84:85], v1 offset:1280
	ds_read_b64_tr_b16 v[32:33], v1 offset:1312
	s_waitcnt lgkmcnt(3)
	v_mfma_f32_16x16x32_bf16 v[22:25], v[74:77], v[100:103], v[204:207]
	ds_read_b64_tr_b16 v[30:31], v1 offset:160
	ds_read_b64_tr_b16 v[74:75], v1 offset:192
	ds_read_b64_tr_b16 v[86:87], v1 offset:224
	ds_read_b64_tr_b16 v[76:77], v1 offset:1344
	ds_read_b64_tr_b16 v[88:89], v1 offset:1376
	ds_read_b64_tr_b16 v[90:91], v1 offset:9216
	s_waitcnt lgkmcnt(7)
	v_mfma_f32_16x16x32_bf16 v[14:17], v[82:85], v[100:103], v[208:211]
	s_waitcnt lgkmcnt(5)
	v_mfma_f32_16x16x32_bf16 v[26:29], v[30:33], v[100:103], v[212:215]
	s_waitcnt lgkmcnt(2)
	v_mfma_f32_16x16x32_bf16 v[74:77], v[74:77], v[100:103], v[216:219]
	ds_read_b64_tr_b16 v[92:93], v1 offset:10368
	s_nop 1
	ds_read_b64_tr_b16 v[84:85], v1 offset:10400
	s_waitcnt lgkmcnt(3)
	v_mfma_f32_16x16x32_bf16 v[2:5], v[86:89], v[100:103], v[220:223]
	ds_read_b64_tr_b16 v[82:83], v1 offset:9248
	s_nop 1
	ds_read_b64_tr_b16 v[30:31], v1 offset:9280
	ds_read_b64_tr_b16 v[86:87], v1 offset:9312
	ds_read_b64_tr_b16 v[32:33], v1 offset:10432
	ds_read_b64_tr_b16 v[88:89], v1 offset:10464
	s_waitcnt lgkmcnt(4)
	v_mfma_f32_16x16x32_bf16 v[10:13], v[82:85], v[104:107], v[10:13]
	ds_read_b64_tr_b16 v[82:83], v1 offset:9344
	ds_read_b64_tr_b16 v[84:85], v1 offset:10496
	v_mfma_f32_16x16x32_bf16 v[6:9], v[90:93], v[104:107], v[6:9]
	s_waitcnt lgkmcnt(3)
; DEV void hgrn_c_unit(Frame& F, int c, int hp) {
;     ...
;     for (int ks = 0; ks < 4; ++ks) { const ab8 qf = *(const ab8*)(qp + 32 * ks);
; #pragma unroll
;         for (int vt = 0; vt < 8; ++vt) { const ab8 sf = tr_frag(Sb, 32 * ks, 32 * vt, n, q4, HC_SROW); acc[vt] = __builtin_amdgcn_mfma_f32_16x16x32_bf16(sf, qf, acc[vt], 0, 0, 0); } }
;     float ss = 0.f;
; #pragma unroll
;     for (int vt = 0; vt < 8; ++vt) ss += (acc[vt][0] * acc[vt][0] + acc[vt][1] * acc[vt][1]) + (acc[vt][2] * acc[vt][2] + acc[vt][3] * acc[vt][3]);
;     ss += __shfl_xor(ss, 16); ss += __shfl_xor(ss, 32);
;     const float rr = 1.0f / sqrtf(ss * (1.f / 128.f) + EPS);
	v_mfma_f32_16x16x32_bf16 v[18:21], v[30:33], v[104:107], v[18:21]
	ds_read_b64_tr_b16 v[30:31], v1 offset:9376
	ds_read_b64_tr_b16 v[90:91], v1 offset:9408
	ds_read_b64_tr_b16 v[94:95], v1 offset:9440
	ds_read_b64_tr_b16 v[32:33], v1 offset:10528
	ds_read_b64_tr_b16 v[92:93], v1 offset:10560
	ds_read_b64_tr_b16 v[96:97], v1 offset:10592
	s_waitcnt lgkmcnt(6)
	v_mfma_f32_16x16x32_bf16 v[14:17], v[82:85], v[104:107], v[14:17]
	v_mfma_f32_16x16x32_bf16 v[22:25], v[86:89], v[104:107], v[22:25]
	s_waitcnt lgkmcnt(2)
	v_mfma_f32_16x16x32_bf16 v[26:29], v[30:33], v[104:107], v[26:29]
	ds_read_b64_tr_b16 v[30:31], v1 offset:18432
	s_waitcnt lgkmcnt(2)
	v_mfma_f32_16x16x32_bf16 v[74:77], v[90:93], v[104:107], v[74:77]
	ds_read_b64_tr_b16 v[32:33], v1 offset:19584
	ds_read_b64_tr_b16 v[92:93], v1 offset:19616
	s_waitcnt lgkmcnt(3)
	v_mfma_f32_16x16x32_bf16 v[2:5], v[94:97], v[104:107], v[2:5]
	ds_read_b64_tr_b16 v[90:91], v1 offset:18464
	ds_read_b64_tr_b16 v[78:79], v1 offset:18496
	ds_read_b64_tr_b16 v[94:95], v1 offset:18528
	ds_read_b64_tr_b16 v[80:81], v1 offset:19648
	ds_read_b64_tr_b16 v[96:97], v1 offset:19680
	s_waitcnt lgkmcnt(6)
	v_mfma_f32_16x16x32_bf16 v[6:9], v[30:33], v[108:111], v[6:9]
	ds_read_b64_tr_b16 v[30:31], v1 offset:18560
	s_waitcnt lgkmcnt(2)
	v_mfma_f32_16x16x32_bf16 v[18:21], v[78:81], v[108:111], v[18:21]
	ds_read_b64_tr_b16 v[32:33], v1 offset:19712
	ds_read_b64_tr_b16 v[80:81], v1 offset:19744
	v_mfma_f32_16x16x32_bf16 v[10:13], v[90:93], v[108:111], v[10:13]
	s_waitcnt lgkmcnt(3)
	v_mfma_f32_16x16x32_bf16 v[90:93], v[94:97], v[108:111], v[22:25]
	ds_read_b64_tr_b16 v[78:79], v1 offset:18592
	s_nop 1
	ds_read_b64_tr_b16 v[22:23], v1 offset:18624
	ds_read_b64_tr_b16 v[94:95], v1 offset:18656
	ds_read_b64_tr_b16 v[24:25], v1 offset:19776
	ds_read_b64_tr_b16 v[96:97], v1 offset:19808
	s_waitcnt lgkmcnt(4)
	v_mfma_f32_16x16x32_bf16 v[78:81], v[78:81], v[108:111], v[26:29]
	s_nop 2
	ds_read_b64_tr_b16 v[26:27], v1 offset:27648
	s_waitcnt lgkmcnt(2)
	v_mfma_f32_16x16x32_bf16 v[74:77], v[22:25], v[108:111], v[74:77]
	ds_read_b64_tr_b16 v[28:29], v1 offset:28800
	ds_read_b64_tr_b16 v[24:25], v1 offset:28832
	v_mfma_f32_16x16x32_bf16 v[14:17], v[30:33], v[108:111], v[14:17]
	s_waitcnt lgkmcnt(3)
	v_mfma_f32_16x16x32_bf16 v[2:5], v[94:97], v[108:111], v[2:5]
	ds_read_b64_tr_b16 v[22:23], v1 offset:27680
	ds_read_b64_tr_b16 v[82:83], v1 offset:27712
	ds_read_b64_tr_b16 v[94:95], v1 offset:27744
	ds_read_b64_tr_b16 v[84:85], v1 offset:28864
	ds_read_b64_tr_b16 v[96:97], v1 offset:28896
	s_waitcnt lgkmcnt(6)
	v_mfma_f32_16x16x32_bf16 v[30:33], v[26:29], v[112:115], v[6:9]
	s_nop 2
	ds_read_b64_tr_b16 v[6:7], v1 offset:27776
	s_waitcnt lgkmcnt(5)
	v_mfma_f32_16x16x32_bf16 v[26:29], v[22:25], v[112:115], v[10:13]
	ds_read_b64_tr_b16 v[8:9], v1 offset:28928
	s_nop 1
	ds_read_b64_tr_b16 v[12:13], v1 offset:28960
	v_mov_b32_e32 v64, v30
	s_nop 2
	v_mov_b32_e32 v65, v26
	s_waitcnt lgkmcnt(4)
	v_mfma_f32_16x16x32_bf16 v[22:25], v[82:85], v[112:115], v[18:21]
	s_waitcnt lgkmcnt(3)
	v_mfma_f32_16x16x32_bf16 v[18:21], v[94:97], v[112:115], v[90:93]
	ds_read_b64_tr_b16 v[10:11], v1 offset:27808
	ds_read_b64_tr_b16 v[82:83], v1 offset:27840
	s_nop 0
	ds_read_b64_tr_b16 v[90:91], v1 offset:27872
	ds_read_b64_tr_b16 v[84:85], v1 offset:28992
	ds_read_b64_tr_b16 v[92:93], v1 offset:29024
	s_nop 1
	v_mul_f32_e32 v50, v19, v19
	s_waitcnt lgkmcnt(6)
	v_mfma_f32_16x16x32_bf16 v[14:17], v[6:9], v[112:115], v[14:17]
	s_waitcnt lgkmcnt(4)
	v_mfma_f32_16x16x32_bf16 v[10:13], v[10:13], v[112:115], v[78:81]
	s_waitcnt lgkmcnt(1)
	v_mfma_f32_16x16x32_bf16 v[6:9], v[82:85], v[112:115], v[74:77]
	s_nop 0
	v_mov_b32_e32 v78, v33
	v_mov_b32_e32 v79, v29
	v_pk_mul_f32 v[80:81], v[24:25], v[24:25]
	v_mov_b32_e32 v74, v31
	v_mov_b32_e32 v75, v27
	v_mov_b32_e32 v76, v32
	v_mov_b32_e32 v77, v28
	v_pk_mul_f32 v[82:83], v[22:23], v[22:23]
	v_pk_mul_f32 v[74:75], v[74:75], v[74:75]
	v_pk_mul_f32 v[78:79], v[78:79], v[78:79]
	v_pk_mov_b32 v[84:85], v[82:83], v[80:81] op_sel:[1,0]
	v_mov_b32_e32 v83, v81
	v_pk_fma_f32 v[64:65], v[64:65], v[64:65], v[74:75]
	v_pk_fma_f32 v[74:75], v[76:77], v[76:77], v[78:79]
	v_pk_add_f32 v[76:77], v[84:85], v[82:83]
	v_pk_add_f32 v[64:65], v[64:65], v[74:75]
	v_mul_f32_e32 v59, v14, v14
	v_mul_f32_e32 v62, v15, v15
	v_pk_add_f32 v[74:75], v[76:77], v[76:77] op_sel:[0,1] op_sel_hi:[1,0]
	v_pk_add_f32 v[64:65], v[64:65], v[64:65] op_sel:[0,1] op_sel_hi:[1,0]
	v_pk_fma_f32 v[80:81], v[18:19], v[18:19], v[50:51] op_sel_hi:[1,1,0]
	v_mov_b32_e32 v75, v62
	v_mov_b32_e32 v65, v59
	v_mul_f32_e32 v50, v21, v21
	s_waitcnt lgkmcnt(0)
	v_mfma_f32_16x16x32_bf16 v[2:5], v[90:93], v[112:115], v[2:5]
	v_mul_f32_e32 v73, v16, v16
	v_mul_f32_e32 v86, v17, v17
	v_pk_add_f32 v[64:65], v[64:65], v[74:75]
	v_pk_fma_f32 v[74:75], v[20:21], v[20:21], v[50:51] op_sel_hi:[1,1,0]
	v_mov_b32_e32 v81, v73
	v_mov_b32_e32 v75, v86
	v_pk_add_f32 v[74:75], v[80:81], v[74:75]
	s_nop 0
	v_mul_f32_e32 v50, v2, v2
	v_pk_add_f32 v[64:65], v[64:65], v[74:75]
	v_pk_mul_f32 v[74:75], v[12:13], v[12:13]
	v_pk_add_f32 v[80:81], v[64:65], v[64:65] op_sel:[0,1] op_sel_hi:[1,0]
	v_pk_mul_f32 v[76:77], v[10:11], v[10:11]
	v_mov_b32_e32 v81, v50
	v_lshlrev_b32_e32 v50, 1, v52
	v_pk_mov_b32 v[78:79], v[76:77], v[74:75] op_sel:[1,0]
	v_mov_b32_e32 v77, v75
	v_pk_add_f32 v[78:79], v[78:79], v[76:77]
	v_mul_f32_e32 v59, v3, v3
	v_pk_add_f32 v[78:79], v[78:79], v[78:79] op_sel:[0,1] op_sel_hi:[1,0]
	v_mul_f32_e32 v62, v7, v7
	v_mov_b32_e32 v79, v59
	v_mul_f32_e32 v73, v4, v4
	v_pk_add_f32 v[78:79], v[80:81], v[78:79]
	v_pk_fma_f32 v[80:81], v[6:7], v[6:7], v[62:63] op_sel_hi:[1,1,0]
	v_mul_f32_e32 v62, v9, v9
	v_mul_f32_e32 v86, v5, v5
	v_mov_b32_e32 v81, v73
	v_pk_fma_f32 v[84:85], v[8:9], v[8:9], v[62:63] op_sel_hi:[1,1,0]
	v_and_b32_e32 v73, 64, v139
	v_mov_b32_e32 v85, v86
	v_xor_b32_e32 v62, 16, v139
	v_add_u32_e32 v73, 64, v73
	v_pk_add_f32 v[80:81], v[80:81], v[84:85]
	v_cmp_lt_i32_e32 vcc, v62, v73
	v_pk_add_f32 v[78:79], v[78:79], v[80:81]
	v_lshl_add_u64 v[60:61], s[8:9], 0, v[60:61]
	v_cndmask_b32_e32 v62, v139, v62, vcc
	v_add_f32_e32 v59, v78, v79
	v_lshlrev_b32_e32 v62, 2, v62
	ds_bpermute_b32 v62, v62, v59
	v_lshl_add_u64 v[60:61], v[60:61], 0, s[16:17]
	v_lshl_add_u64 v[60:61], v[60:61], 0, v[50:51]
	s_waitcnt lgkmcnt(0)
; DEV unsigned cvtpk(float lo, float hi) { typedef float f2 __attribute__((ext_vector_type(2))); typedef __bf16 b2 __attribute__((ext_vector_type(2))); f2 v = {lo, hi}; b2 b = __builtin_convertvector(v, b2); return __builtin_bit_cast(unsigned, b); }
; template <class Tp> DEV Tp* wsp(const Frame& F, size_t off) { return (Tp*)(F.ws + off); }
; DEV void hgrn_c_unit(Frame& F, int c, int hp) {
;     ...
;     ss += __shfl_xor(ss, 16); ss += __shfl_xor(ss, 32);
;     const float rr = 1.0f / sqrtf(ss * (1.f / 128.f) + EPS);
;     const bf16* HG = wsp<bf16>(F, WS_HG) + row * 512 + h * 128 + 4 * q4; bf16* OB = wsp<bf16>(F, WS_OB) + row * 512 + h * 128 + 4 * q4; const float* gn = ((const float*)F.A.in[20]) + 4 * q4;
; #pragma unroll
;     for (int vt = 0; vt < 8; ++vt) { const v2u gw_ = *(const v2u*)(HG + 16 * vt); const f32x4 g4 = *(const f32x4*)(gn + 16 * vt);
;         v2u wv; wv.x = cvtpk(acc[vt][0] * rr * g4[0] * bflo(gw_.x), acc[vt][1] * rr * g4[1] * bfhi(gw_.x)); wv.y = cvtpk(acc[vt][2] * rr * g4[2] * bflo(gw_.y), acc[vt][3] * rr * g4[3] * bfhi(gw_.y));
;         *(v2u*)(OB + 16 * vt) = wv; }
	v_add_f32_e32 v59, v59, v62
	v_xor_b32_e32 v62, 32, v139
	v_cmp_lt_i32_e32 vcc, v62, v73
	s_waitcnt vmcnt(0)
	v_cndmask_b32_e32 v62, v139, v62, vcc
	v_lshlrev_b32_e32 v62, 2, v62
	ds_bpermute_b32 v62, v62, v59
	s_waitcnt lgkmcnt(0)
	v_add_f32_e32 v59, v59, v62
	v_fmamk_f32 v59, v59, 0x3c000000, v71
	v_mul_f32_e32 v62, 0x4f800000, v59
	v_cmp_gt_f32_e32 vcc, s24, v59
	s_nop 1
	v_cndmask_b32_e32 v59, v59, v62, vcc
	v_sqrt_f32_e32 v62, v59
	s_nop 0
	v_add_u32_e32 v73, -1, v62
	v_fma_f32 v78, -v73, v62, v59
	v_cmp_ge_f32_e64 s[4:5], 0, v78
	v_add_u32_e32 v78, 1, v62
	s_nop 0
	v_cndmask_b32_e64 v73, v62, v73, s[4:5]
	v_fma_f32 v62, -v78, v62, v59
	v_cmp_lt_f32_e64 s[4:5], 0, v62
	s_nop 1
	v_cndmask_b32_e64 v62, v73, v78, s[4:5]
	v_mul_f32_e32 v73, 0x37800000, v62
	v_cndmask_b32_e32 v62, v62, v73, vcc
	v_cmp_class_f32_e32 vcc, v59, v72
	s_nop 1
	v_cndmask_b32_e32 v59, v62, v59, vcc
	v_div_scale_f32 v62, s[4:5], v59, v59, 1.0
	v_rcp_f32_e32 v73, v62
	s_mov_b64 s[4:5], -1
	v_fma_f32 v78, -v62, v73, 1.0
	v_fmac_f32_e32 v73, v78, v73
	v_div_scale_f32 v78, vcc, 1.0, v59, 1.0
	v_mul_f32_e32 v79, v78, v73
	v_fma_f32 v80, -v62, v79, v78
	v_fmac_f32_e32 v79, v80, v73
	v_fma_f32 v62, -v62, v79, v78
	v_div_fmas_f32 v62, v62, v73, v79
	v_div_fixup_f32 v62, v62, v59, 1.0
	v_pk_mul_f32 v[30:31], v[30:31], v[62:63] op_sel_hi:[1,0]
	v_pk_mul_f32 v[32:33], v[32:33], v[62:63] op_sel_hi:[1,0]
	v_lshlrev_b32_e32 v140, 16, v116
	v_and_b32_e32 v141, 0xffff0000, v116
	v_lshlrev_b32_e32 v142, 16, v117
	v_and_b32_e32 v143, 0xffff0000, v117
	v_pk_mul_f32 v[30:31], v[160:161], v[30:31]
	v_pk_mul_f32 v[32:33], v[162:163], v[32:33]
	v_pk_mul_f32 v[30:31], v[30:31], v[140:141]
	v_pk_mul_f32 v[32:33], v[32:33], v[142:143]
	v_cvt_pk_bf16_f32 v30, v30, v31
	v_cvt_pk_bf16_f32 v31, v32, v33
	global_store_dwordx2 v[60:61], v[30:31], off
	v_pk_mul_f32 v[26:27], v[26:27], v[62:63] op_sel_hi:[1,0]
	v_pk_mul_f32 v[28:29], v[28:29], v[62:63] op_sel_hi:[1,0]
	v_lshlrev_b32_e32 v144, 16, v118
	v_and_b32_e32 v145, 0xffff0000, v118
	v_lshlrev_b32_e32 v146, 16, v119
	v_and_b32_e32 v147, 0xffff0000, v119
	v_pk_mul_f32 v[26:27], v[164:165], v[26:27]
	v_pk_mul_f32 v[28:29], v[166:167], v[28:29]
	v_pk_mul_f32 v[26:27], v[26:27], v[144:145]
	v_pk_mul_f32 v[28:29], v[28:29], v[146:147]
	v_cvt_pk_bf16_f32 v26, v26, v27
	v_cvt_pk_bf16_f32 v27, v28, v29
	global_store_dwordx2 v[60:61], v[26:27], off offset:32
	v_pk_mul_f32 v[22:23], v[22:23], v[62:63] op_sel_hi:[1,0]
	v_pk_mul_f32 v[24:25], v[24:25], v[62:63] op_sel_hi:[1,0]
	v_lshlrev_b32_e32 v140, 16, v120
	v_and_b32_e32 v141, 0xffff0000, v120
	v_lshlrev_b32_e32 v142, 16, v121
	v_and_b32_e32 v143, 0xffff0000, v121
	v_pk_mul_f32 v[22:23], v[168:169], v[22:23]
	v_pk_mul_f32 v[24:25], v[170:171], v[24:25]
	v_pk_mul_f32 v[22:23], v[22:23], v[140:141]
	v_pk_mul_f32 v[24:25], v[24:25], v[142:143]
	v_cvt_pk_bf16_f32 v22, v22, v23
	v_cvt_pk_bf16_f32 v23, v24, v25
	global_store_dwordx2 v[60:61], v[22:23], off offset:64
	v_pk_mul_f32 v[18:19], v[18:19], v[62:63] op_sel_hi:[1,0]
	v_pk_mul_f32 v[20:21], v[20:21], v[62:63] op_sel_hi:[1,0]
	v_lshlrev_b32_e32 v144, 16, v122
	v_and_b32_e32 v145, 0xffff0000, v122
	v_lshlrev_b32_e32 v146, 16, v123
	v_and_b32_e32 v147, 0xffff0000, v123
	v_pk_mul_f32 v[18:19], v[172:173], v[18:19]
	v_pk_mul_f32 v[20:21], v[174:175], v[20:21]
	v_pk_mul_f32 v[18:19], v[18:19], v[144:145]
	v_pk_mul_f32 v[20:21], v[20:21], v[146:147]
	v_cvt_pk_bf16_f32 v18, v18, v19
	v_cvt_pk_bf16_f32 v19, v20, v21
	global_store_dwordx2 v[60:61], v[18:19], off offset:96
	v_pk_mul_f32 v[14:15], v[14:15], v[62:63] op_sel_hi:[1,0]
	v_pk_mul_f32 v[16:17], v[16:17], v[62:63] op_sel_hi:[1,0]
	v_lshlrev_b32_e32 v140, 16, v124
	v_and_b32_e32 v141, 0xffff0000, v124
	v_lshlrev_b32_e32 v142, 16, v125
	v_and_b32_e32 v143, 0xffff0000, v125
	v_pk_mul_f32 v[14:15], v[176:177], v[14:15]
	v_pk_mul_f32 v[16:17], v[178:179], v[16:17]
	v_pk_mul_f32 v[14:15], v[14:15], v[140:141]
	v_pk_mul_f32 v[16:17], v[16:17], v[142:143]
	v_cvt_pk_bf16_f32 v14, v14, v15
	v_cvt_pk_bf16_f32 v15, v16, v17
	global_store_dwordx2 v[60:61], v[14:15], off offset:128
	v_pk_mul_f32 v[10:11], v[10:11], v[62:63] op_sel_hi:[1,0]
	v_pk_mul_f32 v[12:13], v[12:13], v[62:63] op_sel_hi:[1,0]
	v_lshlrev_b32_e32 v144, 16, v126
	v_and_b32_e32 v145, 0xffff0000, v126
	v_lshlrev_b32_e32 v146, 16, v127
	v_and_b32_e32 v147, 0xffff0000, v127
	v_pk_mul_f32 v[10:11], v[180:181], v[10:11]
	v_pk_mul_f32 v[12:13], v[182:183], v[12:13]
	v_pk_mul_f32 v[10:11], v[10:11], v[144:145]
	v_pk_mul_f32 v[12:13], v[12:13], v[146:147]
	v_cvt_pk_bf16_f32 v10, v10, v11
	v_cvt_pk_bf16_f32 v11, v12, v13
	global_store_dwordx2 v[60:61], v[10:11], off offset:160
	v_pk_mul_f32 v[6:7], v[6:7], v[62:63] op_sel_hi:[1,0]
	v_pk_mul_f32 v[8:9], v[8:9], v[62:63] op_sel_hi:[1,0]
	v_lshlrev_b32_e32 v140, 16, v128
	v_and_b32_e32 v141, 0xffff0000, v128
	v_lshlrev_b32_e32 v142, 16, v129
	v_and_b32_e32 v143, 0xffff0000, v129
	v_pk_mul_f32 v[6:7], v[184:185], v[6:7]
	v_pk_mul_f32 v[8:9], v[186:187], v[8:9]
	v_pk_mul_f32 v[6:7], v[6:7], v[140:141]
	v_pk_mul_f32 v[8:9], v[8:9], v[142:143]
	v_cvt_pk_bf16_f32 v6, v6, v7
	v_cvt_pk_bf16_f32 v7, v8, v9
	global_store_dwordx2 v[60:61], v[6:7], off offset:192
	v_pk_mul_f32 v[2:3], v[2:3], v[62:63] op_sel_hi:[1,0]
	v_pk_mul_f32 v[4:5], v[4:5], v[62:63] op_sel_hi:[1,0]
	v_lshlrev_b32_e32 v144, 16, v130
	v_and_b32_e32 v145, 0xffff0000, v130
	v_lshlrev_b32_e32 v146, 16, v131
	v_and_b32_e32 v147, 0xffff0000, v131
	v_pk_mul_f32 v[2:3], v[188:189], v[2:3]
	v_pk_mul_f32 v[4:5], v[190:191], v[4:5]
	v_pk_mul_f32 v[2:3], v[2:3], v[144:145]
	v_pk_mul_f32 v[4:5], v[4:5], v[146:147]
	v_cvt_pk_bf16_f32 v2, v2, v3
	v_cvt_pk_bf16_f32 v3, v4, v5
	global_store_dwordx2 v[60:61], v[2:3], off offset:224
	s_barrier
